# NA local loop PV reads pipelined; scan stage (a) mask/convert/store epilogue rewritten with sign-normalised compares and paired bf16 stores
# speedup vs baseline: 1.0243x; 1.0044x over previous
.LBB0_432:
	v_sub_f32_e32 v54, v54, v71
	v_sub_f32_e32 v55, v55, v71
	v_exp_f32_e32 v54, v54
	v_exp_f32_e32 v55, v55
	v_sub_f32_e32 v56, v56, v71
	v_sub_f32_e32 v57, v57, v71
	v_exp_f32_e32 v56, v56
	v_exp_f32_e32 v57, v57
	v_sub_f32_e32 v50, v50, v71
	v_sub_f32_e32 v51, v51, v71
	v_exp_f32_e32 v50, v50
	v_exp_f32_e32 v51, v51
	v_sub_f32_e32 v52, v52, v71
	v_sub_f32_e32 v53, v53, v71
	v_exp_f32_e32 v52, v52
	v_exp_f32_e32 v53, v53
	v_pk_add_f32 v[94:95], v[54:55], 0 op_sel_hi:[1,0]
	v_sub_f32_e32 v42, v42, v71
	v_pk_add_f32 v[94:95], v[56:57], v[94:95]
	v_sub_f32_e32 v46, v46, v71
	v_sub_f32_e32 v47, v47, v71
	v_exp_f32_e32 v96, v42
	v_sub_f32_e32 v42, v43, v71
	v_pk_add_f32 v[94:95], v[50:51], v[94:95]
	v_exp_f32_e32 v46, v46
	v_exp_f32_e32 v47, v47
	v_sub_f32_e32 v48, v48, v71
	v_sub_f32_e32 v49, v49, v71
	v_exp_f32_e32 v97, v42
	v_sub_f32_e32 v42, v44, v71
	v_pk_add_f32 v[94:95], v[52:53], v[94:95]
	v_exp_f32_e32 v48, v48
	v_exp_f32_e32 v49, v49
	v_exp_f32_e32 v98, v42
	v_sub_f32_e32 v42, v45, v71
	v_cvt_pk_bf16_f32 v44, v50, v51
	v_cvt_pk_bf16_f32 v45, v52, v53
	ds_read_b128 v[50:53], v0 offset:8192
	ds_read_b128 v[100:103], v93 offset:8192
	ds_read_b128 v[104:107], v0 offset:10240
	ds_read_b128 v[108:111], v93 offset:10240
	ds_read_b128 v[112:115], v0 offset:12288
	v_exp_f32_e32 v99, v42
	v_pk_add_f32 v[94:95], v[46:47], v[94:95]
	v_cvt_pk_bf16_f32 v46, v46, v47
	v_pk_add_f32 v[94:95], v[48:49], v[94:95]
	v_cvt_pk_bf16_f32 v47, v48, v49
	v_pk_add_f32 v[42:43], v[96:97], v[94:95]
	v_cvt_pk_bf16_f32 v48, v96, v97
	v_pk_add_f32 v[42:43], v[98:99], v[42:43]
	v_cvt_pk_bf16_f32 v49, v98, v99
	v_add_f32_e32 v42, v42, v43
	v_add_f32_e32 v68, v68, v42
	v_cvt_pk_bf16_f32 v42, v54, v55
	v_cvt_pk_bf16_f32 v43, v56, v57
	ds_read_b128 v[54:57], v93 offset:12288
	ds_read_b128 v[94:97], v0 offset:14336
	s_addk_i32 s2, 0x4000
	s_and_b32 s0, s2, 0x4000
	s_waitcnt lgkmcnt(6)
	v_mfma_f32_16x16x32_bf16 v[2:5], v[50:53], v[42:45], v[2:5]
	s_add_i32 s0, s0, 0
	s_add_i32 s81, s81, 64
	s_waitcnt lgkmcnt(5)
	v_mfma_f32_16x16x32_bf16 v[2:5], v[100:103], v[46:49], v[2:5]
	s_addk_i32 s80, 0x7c
	s_cmp_eq_u32 s80, 0
	s_waitcnt lgkmcnt(4)
	v_mfma_f32_16x16x32_bf16 v[6:9], v[104:107], v[42:45], v[6:9]
	s_waitcnt lgkmcnt(3)
	v_mfma_f32_16x16x32_bf16 v[6:9], v[108:111], v[46:49], v[6:9]
	s_waitcnt lgkmcnt(2)
	v_mfma_f32_16x16x32_bf16 v[10:13], v[112:115], v[42:45], v[10:13]
	s_waitcnt lgkmcnt(1)
	v_mfma_f32_16x16x32_bf16 v[10:13], v[54:57], v[46:49], v[10:13]
	v_add_u32_e32 v0, s0, v75
	s_waitcnt lgkmcnt(0)
	v_mfma_f32_16x16x32_bf16 v[14:17], v[94:97], v[42:45], v[14:17]
	ds_read_b128 v[42:45], v93 offset:14336
	s_waitcnt vmcnt(3)
	ds_write_b128 v0, v[26:29]
	s_waitcnt vmcnt(2)
	ds_write_b128 v0, v[30:33] offset:4096
	v_add3_u32 v0, s0, v74, v72
	s_waitcnt lgkmcnt(2)
	v_mfma_f32_16x16x32_bf16 v[14:17], v[42:45], v[46:49], v[14:17]
	s_waitcnt vmcnt(1)
	ds_write_b128 v0, v[34:37] offset:8192
	s_waitcnt vmcnt(0)
	ds_write_b128 v0, v[38:41] offset:12288
	s_cbranch_scc1 .LBB0_490
	s_mov_b32 s0, s70
	s_branch .LBB0_408

.LBB0_474:
	v_ashrrev_i32_e32 v0, 6, v89
	v_lshrrev_b32_e32 v90, 4, v89
	v_lshlrev_b32_e32 v74, 8, v92
	v_lshl_add_u32 v93, v0, 12, 0
	v_bitop3_b32 v75, v90, v92, 3 bitop3:0x6c
	v_add_u32_e32 v91, v93, v74
	v_lshlrev_b32_e32 v75, 4, v75
	v_add_u32_e32 v76, v91, v75
	ds_read_b128 v[82:85], v76
	v_add_u32_e32 v118, 0, v74
	v_add_u32_e32 v77, v118, v75
	ds_read_b128 v[78:81], v77 offset:16384
	v_bfe_u32 v119, v89, 4, 2
	s_waitcnt lgkmcnt(0)
	v_mfma_f32_16x16x32_bf16 v[94:97], v[82:85], v[78:81], 0
	ds_read_b128 v[78:81], v77 offset:20480
	ds_read_b128 v[98:101], v77 offset:24576
	ds_read_b128 v[106:109], v77 offset:28672
	v_bitop3_b32 v77, v119, v92, 4 bitop3:0x36
	v_lshlrev_b32_e32 v77, 4, v77
	s_waitcnt lgkmcnt(2)
	v_mfma_f32_16x16x32_bf16 v[102:105], v[82:85], v[78:81], 0
	v_add_u32_e32 v80, v91, v77
	ds_read_b128 v[110:113], v80
	v_add_u32_e32 v78, v118, v77
	s_waitcnt lgkmcnt(2)
	v_mfma_f32_16x16x32_bf16 v[98:101], v[82:85], v[98:101], 0
	v_lshrrev_b32_e32 v89, 3, v89
	s_and_b32 s1, s29, 0x2000
	s_add_i32 s1, s1, 0
	s_waitcnt lgkmcnt(1)
	v_mfma_f32_16x16x32_bf16 v[82:85], v[82:85], v[106:109], 0
	ds_read_b128 v[106:109], v78 offset:16384
	ds_read_b128 v[114:117], v78 offset:20480
	s_mov_b64 s[16:17], -1
	s_waitcnt lgkmcnt(1)
	v_mfma_f32_16x16x32_bf16 v[94:97], v[110:113], v[106:109], v[94:97]
	s_waitcnt lgkmcnt(0)
	v_mfma_f32_16x16x32_bf16 v[102:105], v[110:113], v[114:117], v[102:105]
	ds_read_b128 v[106:109], v78 offset:24576
	ds_read_b128 v[114:117], v78 offset:28672
	v_bitop3_b32 v78, v119, v92, 8 bitop3:0x36
	v_lshlrev_b32_e32 v78, 4, v78
	v_add_u32_e32 v81, v91, v78
	s_waitcnt lgkmcnt(1)
	v_mfma_f32_16x16x32_bf16 v[98:101], v[110:113], v[106:109], v[98:101]
	ds_read_b128 v[106:109], v81
	v_add_u32_e32 v79, v118, v78
	s_waitcnt lgkmcnt(1)
	v_mfma_f32_16x16x32_bf16 v[82:85], v[110:113], v[114:117], v[82:85]
	ds_read_b128 v[110:113], v79 offset:16384
	s_waitcnt lgkmcnt(0)
	v_mfma_f32_16x16x32_bf16 v[94:97], v[106:109], v[110:113], v[94:97]
	ds_read_b128 v[110:113], v79 offset:20480
	ds_read_b128 v[114:117], v79 offset:24576
	s_waitcnt lgkmcnt(1)
	v_mfma_f32_16x16x32_bf16 v[102:105], v[106:109], v[110:113], v[102:105]
	ds_read_b128 v[110:113], v79 offset:28672
	v_bitop3_b32 v79, v119, v92, 12 bitop3:0x36
	v_lshlrev_b32_e32 v79, 4, v79
	v_add_u32_e32 v120, v91, v79
	s_waitcnt lgkmcnt(1)
	v_mfma_f32_16x16x32_bf16 v[98:101], v[106:109], v[114:117], v[98:101]
	ds_read_b128 v[114:117], v120
	v_add_u32_e32 v91, v118, v79
	s_waitcnt lgkmcnt(1)
	v_mfma_f32_16x16x32_bf16 v[106:109], v[106:109], v[110:113], v[82:85]
	s_nop 2
	ds_read_b128 v[82:85], v91 offset:16384
	ds_read_b128 v[110:113], v91 offset:20480
	s_waitcnt lgkmcnt(1)
	v_mfma_f32_16x16x32_bf16 v[94:97], v[114:117], v[82:85], v[94:97]
	s_waitcnt lgkmcnt(0)
	v_mfma_f32_16x16x32_bf16 v[102:105], v[114:117], v[110:113], v[102:105]
	ds_read_b128 v[82:85], v91 offset:24576
	ds_read_b128 v[110:113], v91 offset:28672
	s_waitcnt lgkmcnt(1)
	v_mfma_f32_16x16x32_bf16 v[98:101], v[114:117], v[82:85], v[98:101]
	s_waitcnt lgkmcnt(0)
	v_mfma_f32_16x16x32_bf16 v[106:109], v[114:117], v[110:113], v[106:109]
	v_lshlrev_b32_e32 v83, 2, v119
	v_lshl_or_b32 v82, v0, 4, v83
	v_lshrrev_b32_e32 v84, 3, v92
	v_lshrrev_b32_e32 v85, 1, v83
	v_xor_b32_e32 v85, v85, v84
	v_lshlrev_b32_e32 v85, 4, v85
	v_lshl_add_u32 v84, v82, 7, v85
	v_add_u32_e32 v84, v84, v87
	v_xor_b32_e32 v85, 16, v84
	v_add_u32_e32 v85, 0x100, v85
	v_sub_u32_e32 v112, v92, v82
	v_sub_u32_e32 v113, 0, v112
	v_cndmask_b32_e64 v112, v113, v112, s[4:5]
	v_mov_b32_e32 v113, -16
	v_cndmask_b32_e64 v113, v113, 16, s[4:5]
	v_mov_b32_e32 v114, -1
	v_cndmask_b32_e64 v114, v114, 1, s[4:5]
	v_add_u32_e32 v115, v114, v114
	v_add_u32_e32 v116, v115, v114
	v_cmp_ge_i32_e64 s[98:99], 0, v112
	v_cmp_le_i32_e64 s[100:101], v112, v114
	v_cmp_le_i32_e32 vcc, v112, v115
	v_cndmask_b32_e64 v94, 0, v94, s[98:99]
	v_cndmask_b32_e64 v95, 0, v95, s[100:101]
	v_cmp_le_i32_e64 s[98:99], v112, v116
	v_cndmask_b32_e32 v96, 0, v96, vcc
	v_cvt_pk_bf16_f32 v94, v94, v95
	v_cndmask_b32_e64 v97, 0, v97, s[98:99]
	v_cvt_pk_bf16_f32 v96, v96, v97
	ds_write_b16 v84, v94 offset:53248
	ds_write_b16_d16_hi v84, v94 offset:53376
	ds_write_b16 v85, v96 offset:53248
	ds_write_b16_d16_hi v85, v96 offset:53376
	v_add_u32_e32 v112, v112, v113
	v_xor_b32_e32 v91, 0x20, v84
	v_xor_b32_e32 v110, 0x20, v85
	v_cmp_ge_i32_e64 s[98:99], 0, v112
	v_cmp_le_i32_e64 s[100:101], v112, v114
	v_cmp_le_i32_e32 vcc, v112, v115
	v_cndmask_b32_e64 v102, 0, v102, s[98:99]
	v_cndmask_b32_e64 v103, 0, v103, s[100:101]
	v_cmp_le_i32_e64 s[98:99], v112, v116
	v_cndmask_b32_e32 v104, 0, v104, vcc
	v_cvt_pk_bf16_f32 v102, v102, v103
	v_cndmask_b32_e64 v105, 0, v105, s[98:99]
	v_cvt_pk_bf16_f32 v104, v104, v105
	ds_write_b16 v91, v102 offset:53248
	ds_write_b16_d16_hi v91, v102 offset:53376
	ds_write_b16 v110, v104 offset:53248
	ds_write_b16_d16_hi v110, v104 offset:53376
	v_add_u32_e32 v112, v112, v113
	v_xor_b32_e32 v91, 0x40, v84
	v_xor_b32_e32 v110, 0x40, v85
	v_cmp_ge_i32_e64 s[98:99], 0, v112
	v_cmp_le_i32_e64 s[100:101], v112, v114
	v_cmp_le_i32_e32 vcc, v112, v115
	v_cndmask_b32_e64 v98, 0, v98, s[98:99]
	v_cndmask_b32_e64 v99, 0, v99, s[100:101]
	v_cmp_le_i32_e64 s[98:99], v112, v116
	v_cndmask_b32_e32 v100, 0, v100, vcc
	v_cvt_pk_bf16_f32 v98, v98, v99
	v_cndmask_b32_e64 v101, 0, v101, s[98:99]
	v_cvt_pk_bf16_f32 v100, v100, v101
	ds_write_b16 v91, v98 offset:53248
	ds_write_b16_d16_hi v91, v98 offset:53376
	ds_write_b16 v110, v100 offset:53248
	ds_write_b16_d16_hi v110, v100 offset:53376
	v_add_u32_e32 v112, v112, v113
	v_xor_b32_e32 v91, 0x60, v84
	v_xor_b32_e32 v110, 0x60, v85
	v_cmp_ge_i32_e64 s[98:99], 0, v112
	v_cmp_le_i32_e64 s[100:101], v112, v114
	v_cmp_le_i32_e32 vcc, v112, v115
	v_cndmask_b32_e64 v106, 0, v106, s[98:99]
	v_cndmask_b32_e64 v107, 0, v107, s[100:101]
	v_cmp_le_i32_e64 s[98:99], v112, v116
	v_cndmask_b32_e32 v108, 0, v108, vcc
	v_cvt_pk_bf16_f32 v106, v106, v107
	v_cndmask_b32_e64 v109, 0, v109, s[98:99]
	v_cvt_pk_bf16_f32 v108, v108, v109
	ds_write_b16 v91, v106 offset:53248
	ds_write_b16_d16_hi v91, v106 offset:53376
	ds_write_b16 v110, v108 offset:53248
	ds_write_b16_d16_hi v110, v108 offset:53376
	v_lshlrev_b32_e32 v111, 7, v92
	v_bitop3_b32 v89, v90, v88, 3 bitop3:0x6c
	s_add_i32 s0, 0, 0x13000
	v_lshlrev_b32_e32 v84, 7, v0
	v_lshlrev_b32_e32 v85, 2, v92
	v_add3_u32 v84, s0, v84, v85
	ds_read2_b32 v[84:85], v84 offset1:16
	v_add_u32_e32 v112, 0, v111
	v_lshlrev_b32_e32 v113, 4, v89
	v_add_u32_e32 v114, v112, v113
	ds_read_b128 v[94:97], v114 offset:49152
	s_waitcnt lgkmcnt(1)
	v_pk_mul_f32 v[40:41], v[40:41], v[84:85] op_sel_hi:[1,0]
	v_pk_mul_f32 v[38:39], v[38:39], v[84:85] op_sel_hi:[1,0]
	v_pk_mul_f32 v[48:49], v[48:49], v[84:85] op_sel_hi:[1,0]
	v_pk_mul_f32 v[46:47], v[46:47], v[84:85] op_sel_hi:[1,0]
	v_bitop3_b32 v84, v119, v88, 4 bitop3:0x36
	v_add3_u32 v89, v93, v113, v111
	v_lshlrev_b32_e32 v84, 4, v84
	ds_read_b128 v[98:101], v89 offset:32768
	ds_read_b128 v[102:105], v114 offset:51200
	ds_read_b128 v[106:109], v89 offset:34816
	v_mov_b32_e32 v110, v85
	v_add_u32_e32 v85, v112, v84
	ds_read_b128 v[88:91], v85 offset:49152
	v_pk_mul_f32 v[44:45], v[44:45], v[110:111] op_sel_hi:[1,0]
	v_pk_mul_f32 v[42:43], v[42:43], v[110:111] op_sel_hi:[1,0]
	v_pk_mul_f32 v[52:53], v[52:53], v[110:111] op_sel_hi:[1,0]
	v_pk_mul_f32 v[50:51], v[50:51], v[110:111] op_sel_hi:[1,0]
	v_add3_u32 v93, v93, v84, v111
	s_waitcnt lgkmcnt(3)
	v_mfma_f32_16x16x32_bf16 v[38:41], v[94:97], v[98:101], v[38:41]
	s_add_i32 s0, s29, 0xffffe000
	s_and_b32 s0, s0, 0x2000
	s_andn2_b64 vcc, exec, s[8:9]
	s_waitcnt lgkmcnt(1)
	v_mfma_f32_16x16x32_bf16 v[42:45], v[94:97], v[106:109], v[42:45]
	v_mfma_f32_16x16x32_bf16 v[46:49], v[102:105], v[98:101], v[46:49]
	v_mfma_f32_16x16x32_bf16 v[50:53], v[102:105], v[106:109], v[50:53]
	ds_read_b128 v[94:97], v93 offset:32768
	ds_read_b128 v[98:101], v85 offset:51200
	ds_read_b128 v[102:105], v93 offset:34816
	s_waitcnt lgkmcnt(2)
	v_mfma_f32_16x16x32_bf16 v[38:41], v[88:91], v[94:97], v[38:41]
	s_waitcnt lgkmcnt(0)
	v_mfma_f32_16x16x32_bf16 v[42:45], v[88:91], v[102:105], v[42:45]
	v_lshl_or_b32 v88, v0, 5, v92
	v_lshrrev_b32_e32 v88, 3, v88
	v_or_b32_e32 v89, 1, v83
	v_mfma_f32_16x16x32_bf16 v[46:49], v[98:101], v[94:97], v[46:49]
	v_xor_b32_e32 v95, v88, v83
	v_lshlrev_b32_e32 v95, 4, v95
	v_lshlrev_b32_e32 v94, 10, v119
	v_add3_u32 v95, s1, v95, v87
	v_bitop3_b32 v97, v83, v88, 1 bitop3:0x36
	v_cvt_pk_bf16_f32 v93, v38, s0
	v_add_u32_e32 v96, v95, v94
	v_lshlrev_b32_e32 v97, 4, v97
	ds_write_b16 v96, v93 offset:61440
	v_lshlrev_b32_e32 v96, 8, v89
	v_add3_u32 v97, s1, v97, v87
	v_mfma_f32_16x16x32_bf16 v[50:53], v[98:101], v[102:105], v[50:53]
	v_cvt_pk_bf16_f32 v93, v39, s0
	v_add_u32_e32 v98, v97, v96
	ds_write_b16 v98, v93 offset:61440
	v_bitop3_b32 v98, v83, v88, 2 bitop3:0x36
	v_or_b32_e32 v90, 2, v83
	v_lshlrev_b32_e32 v98, 4, v98
	v_lshlrev_b32_e32 v90, 8, v90
	v_add3_u32 v98, s1, v98, v87
	v_bitop3_b32 v100, v83, v88, 3 bitop3:0x36
	v_or_b32_e32 v91, 3, v83
	v_cvt_pk_bf16_f32 v93, v40, s0
	v_add_u32_e32 v99, v98, v90
	v_lshlrev_b32_e32 v100, 4, v100
	ds_write_b16 v99, v93 offset:61440
	v_lshlrev_b32_e32 v99, 8, v91
	v_add3_u32 v100, s1, v100, v87
	v_cvt_pk_bf16_f32 v93, v41, s0
	v_add_u32_e32 v101, v100, v99
	ds_write_b16 v101, v93 offset:61440
	v_bitop3_b32 v101, v88, v83, 2 bitop3:0x36
	v_lshlrev_b32_e32 v101, 4, v101
	v_bitop3_b32 v89, v88, v89, 2 bitop3:0x36
	v_add3_u32 v101, s1, v101, v87
	v_lshlrev_b32_e32 v89, 4, v89
	v_bitop3_b32 v83, v88, v83, 2 bitop3:0x14
	v_cvt_pk_bf16_f32 v93, v42, s0
	v_add_u32_e32 v102, v101, v94
	v_add3_u32 v89, s1, v89, v87
	v_lshlrev_b32_e32 v83, 4, v83
	v_bitop3_b32 v88, v88, v91, 2 bitop3:0x36
	ds_write_b16 v102, v93 offset:61440
	v_cvt_pk_bf16_f32 v93, v43, s0
	v_add_u32_e32 v96, v89, v96
	v_add3_u32 v83, s1, v83, v87
	v_lshlrev_b32_e32 v88, 4, v88
	ds_write_b16 v96, v93 offset:61440
	v_cvt_pk_bf16_f32 v93, v44, s0
	v_add_u32_e32 v90, v83, v90
	v_add3_u32 v87, s1, v88, v87
	ds_write_b16 v90, v93 offset:61440
	v_cvt_pk_bf16_f32 v90, v45, s0
	v_add_u32_e32 v88, v87, v99
	ds_write_b16 v88, v90 offset:61440
	v_or_b32_e32 v90, 0x1000, v94
	v_cvt_pk_bf16_f32 v88, v46, s0
	v_add_u32_e32 v91, v95, v90
	ds_write_b16 v91, v88 offset:61440
	v_or_b32_e32 v91, 0x1100, v94
	v_cvt_pk_bf16_f32 v88, v47, s0
	v_add_u32_e32 v93, v97, v91
	ds_write_b16 v93, v88 offset:61440
	v_or_b32_e32 v93, 0x1200, v94
	v_cvt_pk_bf16_f32 v88, v48, s0
	v_add_u32_e32 v95, v98, v93
	v_or_b32_e32 v94, 0x1300, v94
	ds_write_b16 v95, v88 offset:61440
	v_cvt_pk_bf16_f32 v88, v49, s0
	v_add_u32_e32 v95, v100, v94
	ds_write_b16 v95, v88 offset:61440
	v_cvt_pk_bf16_f32 v88, v50, s0
	v_add_u32_e32 v90, v101, v90
	ds_write_b16 v90, v88 offset:61440
	v_cvt_pk_bf16_f32 v88, v51, s0
	v_add_u32_e32 v89, v89, v91
	ds_write_b16 v89, v88 offset:61440
	v_cvt_pk_bf16_f32 v88, v52, s0
	v_add_u32_e32 v83, v83, v93
	ds_write_b16 v83, v88 offset:61440
	v_cvt_pk_bf16_f32 v83, v53, s0
	v_add_u32_e32 v87, v87, v94
	ds_write_b16 v87, v83 offset:61440
	s_waitcnt lgkmcnt(0)
	s_barrier
	ds_read_b128 v[88:91], v76
	s_add_i32 s0, s0, 0
	v_add_u32_e32 v83, s0, v74
	v_add_u32_e32 v74, v83, v75
	ds_read_b128 v[94:97], v74 offset:61440
	v_add_u32_e32 v74, 0xf000, v74
	ds_read_b128 v[98:101], v74 offset:4096
	ds_read_b128 v[102:105], v80
	v_add_u32_e32 v80, v83, v77
	ds_read_b128 v[74:77], v80 offset:61440
	s_waitcnt lgkmcnt(3)
	v_mfma_f32_16x16x32_bf16 v[94:97], v[88:91], v[94:97], 0
	v_add_u32_e32 v78, v83, v78
	ds_read_b128 v[106:109], v78 offset:61440
	v_add_u32_e32 v80, 0xf000, v80
	s_waitcnt lgkmcnt(3)
	v_mfma_f32_16x16x32_bf16 v[88:91], v[88:91], v[98:101], 0
	ds_read_b128 v[98:101], v80 offset:4096
	v_add_u32_e32 v78, 0xf000, v78
	v_add_u32_e32 v83, v83, v79
	s_waitcnt lgkmcnt(2)
	v_mfma_f32_16x16x32_bf16 v[74:77], v[102:105], v[74:77], v[94:97]
	v_lshl_add_u32 v0, v0, 11, v112
	s_nop 1
	ds_read_b128 v[94:97], v81
	s_waitcnt lgkmcnt(1)
	v_mfma_f32_16x16x32_bf16 v[88:91], v[102:105], v[98:101], v[88:91]
	ds_read_b128 v[98:101], v78 offset:4096
	ds_read_b128 v[102:105], v120
	ds_read_b128 v[78:81], v83 offset:61440
	v_add_u32_e32 v83, 0xf000, v83
	s_waitcnt lgkmcnt(3)
	v_mfma_f32_16x16x32_bf16 v[74:77], v[94:97], v[106:109], v[74:77]
	s_waitcnt lgkmcnt(2)
	v_mfma_f32_16x16x32_bf16 v[88:91], v[94:97], v[98:101], v[88:91]
	ds_read_b128 v[94:97], v83 offset:4096
	s_waitcnt lgkmcnt(1)
	v_mfma_f32_16x16x32_bf16 v[74:77], v[102:105], v[78:81], v[74:77]
	v_add_u32_e32 v78, v0, v113
	ds_read_b128 v[78:81], v78 offset:53248
	ds_read_b128 v[98:101], v114 offset:49152
	v_add_u32_e32 v0, v0, v84
	s_waitcnt lgkmcnt(2)
	v_mfma_f32_16x16x32_bf16 v[88:91], v[102:105], v[94:97], v[88:91]
	ds_read_b128 v[94:97], v114 offset:51200
	ds_read_b128 v[102:105], v0 offset:53248
	v_cndmask_b32_e64 v0, 0, 1, s[8:9]
	s_waitcnt lgkmcnt(2)
	v_mfma_f32_16x16x32_bf16 v[74:77], v[78:81], v[98:101], v[74:77]
	v_add_u32_e32 v84, s30, v82
	v_cmp_ne_u32_e64 s[6:7], 1, v0
	s_waitcnt lgkmcnt(1)
	v_mfma_f32_16x16x32_bf16 v[88:91], v[78:81], v[94:97], v[88:91]
	ds_read_b128 v[78:81], v85 offset:49152
	ds_read_b128 v[94:97], v85 offset:51200
	s_waitcnt lgkmcnt(1)
	v_mfma_f32_16x16x32_bf16 v[78:81], v[102:105], v[78:81], v[74:77]
	s_waitcnt lgkmcnt(0)
	v_mfma_f32_16x16x32_bf16 v[74:77], v[102:105], v[94:97], v[88:91]
	s_cbranch_vccnz .LBB0_476
	v_ashrrev_i32_e32 v82, 1, v84
	v_ashrrev_i32_e32 v83, 31, v82
	v_lshlrev_b64 v[82:83], 12, v[82:83]
	v_lshl_add_u64 v[82:83], s[12:13], 0, v[82:83]
	s_mov_b64 s[16:17], 0
